# P10 g_final loads batched (no per-chunk vmcnt0 ladder); P4b prompt-diff loop 4 rows in flight
# speedup vs baseline: 1.0022x; 1.0022x over previous
.LBB0_1256:
	v_mov_b32_e32 v70, v9
	v_add_u32_e32 v71, s2, v70
	v_add_u32_e32 v72, s2, v71
	v_add_u32_e32 v73, s2, v72
	v_ashrrev_i32_e32 v18, 3, v70
	v_ashrrev_i32_e32 v19, 31, v18
	v_lshlrev_b64 v[18:19], 12, v[18:19]
	v_lshl_add_u64 v[20:21], v[10:11], 0, v[18:19]
	v_cmp_ge_i32_e32 vcc, s7, v70
	v_lshl_or_b32 v18, v8, 1, v18
	v_lshl_add_u64 v[24:25], s[38:39], 0, v[18:19]
	v_lshl_add_u64 v[38:39], s[44:45], 0, v[18:19]
	s_and_saveexec_b64 s[8:9], vcc
	global_load_dwordx2 v[32:33], v[20:21], off
	global_load_dwordx2 v[34:35], v[20:21], off offset:256
	global_load_dwordx2 v[36:37], v[24:25], off
	s_mov_b64 exec, s[8:9]
	v_ashrrev_i32_e32 v18, 3, v71
	v_ashrrev_i32_e32 v19, 31, v18
	v_lshlrev_b64 v[18:19], 12, v[18:19]
	v_lshl_add_u64 v[20:21], v[10:11], 0, v[18:19]
	v_cmp_ge_i32_e32 vcc, s7, v71
	v_lshl_or_b32 v18, v8, 1, v18
	v_lshl_add_u64 v[24:25], s[38:39], 0, v[18:19]
	v_lshl_add_u64 v[48:49], s[44:45], 0, v[18:19]
	s_and_saveexec_b64 s[8:9], vcc
	global_load_dwordx2 v[42:43], v[20:21], off
	global_load_dwordx2 v[44:45], v[20:21], off offset:256
	global_load_dwordx2 v[46:47], v[24:25], off
	s_mov_b64 exec, s[8:9]
	v_ashrrev_i32_e32 v18, 3, v72
	v_ashrrev_i32_e32 v19, 31, v18
	v_lshlrev_b64 v[18:19], 12, v[18:19]
	v_lshl_add_u64 v[20:21], v[10:11], 0, v[18:19]
	v_cmp_ge_i32_e32 vcc, s7, v72
	v_lshl_or_b32 v18, v8, 1, v18
	v_lshl_add_u64 v[24:25], s[38:39], 0, v[18:19]
	v_lshl_add_u64 v[58:59], s[44:45], 0, v[18:19]
	s_and_saveexec_b64 s[8:9], vcc
	global_load_dwordx2 v[52:53], v[20:21], off
	global_load_dwordx2 v[54:55], v[20:21], off offset:256
	global_load_dwordx2 v[56:57], v[24:25], off
	s_mov_b64 exec, s[8:9]
	v_ashrrev_i32_e32 v18, 3, v73
	v_ashrrev_i32_e32 v19, 31, v18
	v_lshlrev_b64 v[18:19], 12, v[18:19]
	v_lshl_add_u64 v[20:21], v[10:11], 0, v[18:19]
	v_cmp_ge_i32_e32 vcc, s7, v73
	v_lshl_or_b32 v18, v8, 1, v18
	v_lshl_add_u64 v[24:25], s[38:39], 0, v[18:19]
	v_lshl_add_u64 v[68:69], s[44:45], 0, v[18:19]
	s_and_saveexec_b64 s[8:9], vcc
	global_load_dwordx2 v[62:63], v[20:21], off
	global_load_dwordx2 v[64:65], v[20:21], off offset:256
	global_load_dwordx2 v[66:67], v[24:25], off
	s_mov_b64 exec, s[8:9]
	s_waitcnt vmcnt(9)
	v_lshlrev_b32_e32 v26, 16, v32
	v_and_b32_e32 v27, 0xffff0000, v32
	v_lshlrev_b32_e32 v28, 16, v34
	v_and_b32_e32 v29, 0xffff0000, v34
	v_lshlrev_b32_e32 v22, 16, v33
	v_and_b32_e32 v23, 0xffff0000, v33
	v_lshlrev_b32_e32 v20, 16, v35
	v_and_b32_e32 v21, 0xffff0000, v35
	v_pk_fma_f32 v[26:27], v[4:5], v[28:29], v[26:27] neg_lo:[1,0,0] neg_hi:[1,0,0]
	v_pk_fma_f32 v[20:21], v[12:13], v[20:21], v[22:23]
	v_pk_mul_f32 v[30:31], v[26:27], v[26:27]
	v_pk_mul_f32 v[28:29], v[20:21], v[20:21]
	v_add_f32_e32 v30, v30, v31
	v_add_f32_e32 v28, v28, v30
	v_add_f32_e32 v28, v29, v28
	ds_bpermute_b32 v29, v252, v28
	v_lshlrev_b32_e32 v22, 16, v36
	v_and_b32_e32 v23, 0xffff0000, v36
	v_lshlrev_b32_e32 v24, 16, v37
	v_and_b32_e32 v25, 0xffff0000, v37
	s_waitcnt lgkmcnt(0)
	v_add_f32_e32 v28, v28, v29
	ds_bpermute_b32 v29, v251, v28
	s_waitcnt lgkmcnt(0)
	v_add_f32_e32 v28, v28, v29
	ds_bpermute_b32 v29, v249, v28
	s_waitcnt lgkmcnt(0)
	v_add_f32_e32 v28, v28, v29
	ds_bpermute_b32 v29, v248, v28
	s_waitcnt lgkmcnt(0)
	v_add_f32_e32 v28, v28, v29
	ds_bpermute_b32 v29, v247, v28
	s_waitcnt lgkmcnt(0)
	v_add_f32_e32 v28, v28, v29
	v_fmamk_f32 v28, v28, 0x3c000000, v7
	v_mul_f32_e32 v29, 0x4b800000, v28
	v_cmp_gt_f32_e32 vcc, s6, v28
	s_nop 1
	v_cndmask_b32_e32 v28, v28, v29, vcc
	v_rsq_f32_e32 v28, v28
	s_nop 0
	v_mul_f32_e32 v29, 0x45800000, v28
	v_cndmask_b32_e32 v28, v28, v29, vcc
	v_pk_mul_f32 v[20:21], v[20:21], v[28:29] op_sel_hi:[1,0]
	v_pk_mul_f32 v[26:27], v[26:27], v[28:29] op_sel_hi:[1,0]
	v_pk_mul_f32 v[20:21], v[0:1], v[20:21]
	v_pk_mul_f32 v[26:27], v[2:3], v[26:27]
	v_pk_mul_f32 v[20:21], v[20:21], v[24:25]
	v_pk_mul_f32 v[22:23], v[26:27], v[22:23]
	v_cmp_ge_i32_e32 vcc, s7, v70
	v_cvt_pk_bf16_f32 v22, v22, v23
	v_cvt_pk_bf16_f32 v23, v20, v21
	s_and_saveexec_b64 s[8:9], vcc
	global_store_dwordx2 v[38:39], v[22:23], off
	s_mov_b64 exec, s[8:9]
	s_waitcnt vmcnt(7)
	v_lshlrev_b32_e32 v26, 16, v42
	v_and_b32_e32 v27, 0xffff0000, v42
	v_lshlrev_b32_e32 v28, 16, v44
	v_and_b32_e32 v29, 0xffff0000, v44
	v_lshlrev_b32_e32 v22, 16, v43
	v_and_b32_e32 v23, 0xffff0000, v43
	v_lshlrev_b32_e32 v20, 16, v45
	v_and_b32_e32 v21, 0xffff0000, v45
	v_pk_fma_f32 v[26:27], v[4:5], v[28:29], v[26:27] neg_lo:[1,0,0] neg_hi:[1,0,0]
	v_pk_fma_f32 v[20:21], v[12:13], v[20:21], v[22:23]
	v_pk_mul_f32 v[30:31], v[26:27], v[26:27]
	v_pk_mul_f32 v[28:29], v[20:21], v[20:21]
	v_add_f32_e32 v30, v30, v31
	v_add_f32_e32 v28, v28, v30
	v_add_f32_e32 v28, v29, v28
	ds_bpermute_b32 v29, v252, v28
	v_lshlrev_b32_e32 v22, 16, v46
	v_and_b32_e32 v23, 0xffff0000, v46
	v_lshlrev_b32_e32 v24, 16, v47
	v_and_b32_e32 v25, 0xffff0000, v47
	s_waitcnt lgkmcnt(0)
	v_add_f32_e32 v28, v28, v29
	ds_bpermute_b32 v29, v251, v28
	s_waitcnt lgkmcnt(0)
	v_add_f32_e32 v28, v28, v29
	ds_bpermute_b32 v29, v249, v28
	s_waitcnt lgkmcnt(0)
	v_add_f32_e32 v28, v28, v29
	ds_bpermute_b32 v29, v248, v28
	s_waitcnt lgkmcnt(0)
	v_add_f32_e32 v28, v28, v29
	ds_bpermute_b32 v29, v247, v28
	s_waitcnt lgkmcnt(0)
	v_add_f32_e32 v28, v28, v29
	v_fmamk_f32 v28, v28, 0x3c000000, v7
	v_mul_f32_e32 v29, 0x4b800000, v28
	v_cmp_gt_f32_e32 vcc, s6, v28
	s_nop 1
	v_cndmask_b32_e32 v28, v28, v29, vcc
	v_rsq_f32_e32 v28, v28
	s_nop 0
	v_mul_f32_e32 v29, 0x45800000, v28
	v_cndmask_b32_e32 v28, v28, v29, vcc
	v_pk_mul_f32 v[20:21], v[20:21], v[28:29] op_sel_hi:[1,0]
	v_pk_mul_f32 v[26:27], v[26:27], v[28:29] op_sel_hi:[1,0]
	v_pk_mul_f32 v[20:21], v[0:1], v[20:21]
	v_pk_mul_f32 v[26:27], v[2:3], v[26:27]
	v_pk_mul_f32 v[20:21], v[20:21], v[24:25]
	v_pk_mul_f32 v[22:23], v[26:27], v[22:23]
	v_cmp_ge_i32_e32 vcc, s7, v71
	v_cvt_pk_bf16_f32 v22, v22, v23
	v_cvt_pk_bf16_f32 v23, v20, v21
	s_and_saveexec_b64 s[8:9], vcc
	global_store_dwordx2 v[48:49], v[22:23], off
	s_mov_b64 exec, s[8:9]
	s_waitcnt vmcnt(5)
	v_lshlrev_b32_e32 v26, 16, v52
	v_and_b32_e32 v27, 0xffff0000, v52
	v_lshlrev_b32_e32 v28, 16, v54
	v_and_b32_e32 v29, 0xffff0000, v54
	v_lshlrev_b32_e32 v22, 16, v53
	v_and_b32_e32 v23, 0xffff0000, v53
	v_lshlrev_b32_e32 v20, 16, v55
	v_and_b32_e32 v21, 0xffff0000, v55
	v_pk_fma_f32 v[26:27], v[4:5], v[28:29], v[26:27] neg_lo:[1,0,0] neg_hi:[1,0,0]
	v_pk_fma_f32 v[20:21], v[12:13], v[20:21], v[22:23]
	v_pk_mul_f32 v[30:31], v[26:27], v[26:27]
	v_pk_mul_f32 v[28:29], v[20:21], v[20:21]
	v_add_f32_e32 v30, v30, v31
	v_add_f32_e32 v28, v28, v30
	v_add_f32_e32 v28, v29, v28
	ds_bpermute_b32 v29, v252, v28
	v_lshlrev_b32_e32 v22, 16, v56
	v_and_b32_e32 v23, 0xffff0000, v56
	v_lshlrev_b32_e32 v24, 16, v57
	v_and_b32_e32 v25, 0xffff0000, v57
	s_waitcnt lgkmcnt(0)
	v_add_f32_e32 v28, v28, v29
	ds_bpermute_b32 v29, v251, v28
	s_waitcnt lgkmcnt(0)
	v_add_f32_e32 v28, v28, v29
	ds_bpermute_b32 v29, v249, v28
	s_waitcnt lgkmcnt(0)
	v_add_f32_e32 v28, v28, v29
	ds_bpermute_b32 v29, v248, v28
	s_waitcnt lgkmcnt(0)
	v_add_f32_e32 v28, v28, v29
	ds_bpermute_b32 v29, v247, v28
	s_waitcnt lgkmcnt(0)
	v_add_f32_e32 v28, v28, v29
	v_fmamk_f32 v28, v28, 0x3c000000, v7
	v_mul_f32_e32 v29, 0x4b800000, v28
	v_cmp_gt_f32_e32 vcc, s6, v28
	s_nop 1
	v_cndmask_b32_e32 v28, v28, v29, vcc
	v_rsq_f32_e32 v28, v28
	s_nop 0
	v_mul_f32_e32 v29, 0x45800000, v28
	v_cndmask_b32_e32 v28, v28, v29, vcc
	v_pk_mul_f32 v[20:21], v[20:21], v[28:29] op_sel_hi:[1,0]
	v_pk_mul_f32 v[26:27], v[26:27], v[28:29] op_sel_hi:[1,0]
	v_pk_mul_f32 v[20:21], v[0:1], v[20:21]
	v_pk_mul_f32 v[26:27], v[2:3], v[26:27]
	v_pk_mul_f32 v[20:21], v[20:21], v[24:25]
	v_pk_mul_f32 v[22:23], v[26:27], v[22:23]
	v_cmp_ge_i32_e32 vcc, s7, v72
	v_cvt_pk_bf16_f32 v22, v22, v23
	v_cvt_pk_bf16_f32 v23, v20, v21
	s_and_saveexec_b64 s[8:9], vcc
	global_store_dwordx2 v[58:59], v[22:23], off
	s_mov_b64 exec, s[8:9]
	s_waitcnt vmcnt(3)
	v_lshlrev_b32_e32 v26, 16, v62
	v_and_b32_e32 v27, 0xffff0000, v62
	v_lshlrev_b32_e32 v28, 16, v64
	v_and_b32_e32 v29, 0xffff0000, v64
	v_lshlrev_b32_e32 v22, 16, v63
	v_and_b32_e32 v23, 0xffff0000, v63
	v_lshlrev_b32_e32 v20, 16, v65
	v_and_b32_e32 v21, 0xffff0000, v65
	v_pk_fma_f32 v[26:27], v[4:5], v[28:29], v[26:27] neg_lo:[1,0,0] neg_hi:[1,0,0]
	v_pk_fma_f32 v[20:21], v[12:13], v[20:21], v[22:23]
	v_pk_mul_f32 v[30:31], v[26:27], v[26:27]
	v_pk_mul_f32 v[28:29], v[20:21], v[20:21]
	v_add_f32_e32 v30, v30, v31
	v_add_f32_e32 v28, v28, v30
	v_add_f32_e32 v28, v29, v28
	ds_bpermute_b32 v29, v252, v28
	v_lshlrev_b32_e32 v22, 16, v66
	v_and_b32_e32 v23, 0xffff0000, v66
	v_lshlrev_b32_e32 v24, 16, v67
	v_and_b32_e32 v25, 0xffff0000, v67
	s_waitcnt lgkmcnt(0)
	v_add_f32_e32 v28, v28, v29
	ds_bpermute_b32 v29, v251, v28
	s_waitcnt lgkmcnt(0)
	v_add_f32_e32 v28, v28, v29
	ds_bpermute_b32 v29, v249, v28
	s_waitcnt lgkmcnt(0)
	v_add_f32_e32 v28, v28, v29
	ds_bpermute_b32 v29, v248, v28
	s_waitcnt lgkmcnt(0)
	v_add_f32_e32 v28, v28, v29
	ds_bpermute_b32 v29, v247, v28
	s_waitcnt lgkmcnt(0)
	v_add_f32_e32 v28, v28, v29
	v_fmamk_f32 v28, v28, 0x3c000000, v7
	v_mul_f32_e32 v29, 0x4b800000, v28
	v_cmp_gt_f32_e32 vcc, s6, v28
	s_nop 1
	v_cndmask_b32_e32 v28, v28, v29, vcc
	v_rsq_f32_e32 v28, v28
	s_nop 0
	v_mul_f32_e32 v29, 0x45800000, v28
	v_cndmask_b32_e32 v28, v28, v29, vcc
	v_pk_mul_f32 v[20:21], v[20:21], v[28:29] op_sel_hi:[1,0]
	v_pk_mul_f32 v[26:27], v[26:27], v[28:29] op_sel_hi:[1,0]
	v_pk_mul_f32 v[20:21], v[0:1], v[20:21]
	v_pk_mul_f32 v[26:27], v[2:3], v[26:27]
	v_pk_mul_f32 v[20:21], v[20:21], v[24:25]
	v_pk_mul_f32 v[22:23], v[26:27], v[22:23]
	v_cmp_ge_i32_e32 vcc, s7, v73
	v_cvt_pk_bf16_f32 v22, v22, v23
	v_cvt_pk_bf16_f32 v23, v20, v21
	s_and_saveexec_b64 s[8:9], vcc
	global_store_dwordx2 v[68:69], v[22:23], off
	s_mov_b64 exec, s[8:9]
	v_add_u32_e32 v9, s2, v73
	v_cmp_lt_i32_e32 vcc, s7, v9
	s_or_b64 s[4:5], vcc, s[4:5]
	s_andn2_b64 exec, exec, s[4:5]
	s_cbranch_execnz .LBB0_1256
